# P6 relaxed first waits moved into a peeled copy of the first K-loop iteration (loop body untouched)
# baseline (speedup 1.0000x reference)
.LBB0_779:
	s_ashr_i32 s43, s42, 31
	s_lshl_b64 s[6:7], s[42:43], 19
	s_add_u32 s44, s18, s6
	s_addc_u32 s45, s19, s7
	s_and_b64 s[6:7], s[0:1], exec
	s_cselect_b32 s43, s45, s49
	s_cselect_b32 s78, s44, s48
	s_ashr_i32 s39, s38, 31
	s_lshl_b64 s[6:7], s[38:39], 19
	s_add_u32 s46, s34, s6
	s_addc_u32 s47, s35, s7
	s_and_b64 s[6:7], s[0:1], exec
	s_cselect_b32 s39, s47, s51
	s_cselect_b32 s79, s46, s50
	s_add_u32 s48, s48, 0x40080
	s_addc_u32 s49, s49, 0
	s_add_u32 s80, s50, 0x100
	v_mov_b32_e32 v2, 0
	s_addc_u32 s81, s51, 0
	s_mov_b32 s82, -2
	v_mov_b32_e32 v3, v2
	v_mov_b32_e32 v4, v2
	v_mov_b32_e32 v5, v2
	v_mov_b32_e32 v6, v2
	v_mov_b32_e32 v7, v2
	v_mov_b32_e32 v8, v2
	v_mov_b32_e32 v9, v2
	v_mov_b32_e32 v18, v2
	v_mov_b32_e32 v19, v2
	v_mov_b32_e32 v20, v2
	v_mov_b32_e32 v21, v2
	v_mov_b32_e32 v22, v2
	v_mov_b32_e32 v23, v2
	v_mov_b32_e32 v24, v2
	v_mov_b32_e32 v25, v2
	v_mov_b32_e32 v34, v2
	v_mov_b32_e32 v35, v2
	v_mov_b32_e32 v36, v2
	v_mov_b32_e32 v37, v2
	v_mov_b32_e32 v38, v2
	v_mov_b32_e32 v39, v2
	v_mov_b32_e32 v40, v2
	v_mov_b32_e32 v41, v2
	v_mov_b32_e32 v50, v2
	v_mov_b32_e32 v51, v2
	v_mov_b32_e32 v52, v2
	v_mov_b32_e32 v53, v2
	v_mov_b32_e32 v54, v2
	v_mov_b32_e32 v55, v2
	v_mov_b32_e32 v56, v2
	v_mov_b32_e32 v57, v2
	v_mov_b32_e32 v10, v2
	v_mov_b32_e32 v11, v2
	v_mov_b32_e32 v12, v2
	v_mov_b32_e32 v13, v2
	v_mov_b32_e32 v14, v2
	v_mov_b32_e32 v15, v2
	v_mov_b32_e32 v16, v2
	v_mov_b32_e32 v17, v2
	v_mov_b32_e32 v26, v2
	v_mov_b32_e32 v27, v2
	v_mov_b32_e32 v28, v2
	v_mov_b32_e32 v29, v2
	v_mov_b32_e32 v30, v2
	v_mov_b32_e32 v31, v2
	v_mov_b32_e32 v32, v2
	v_mov_b32_e32 v33, v2
	v_mov_b32_e32 v42, v2
	v_mov_b32_e32 v43, v2
	v_mov_b32_e32 v44, v2
	v_mov_b32_e32 v45, v2
	v_mov_b32_e32 v46, v2
	v_mov_b32_e32 v47, v2
	v_mov_b32_e32 v48, v2
	v_mov_b32_e32 v49, v2
	v_mov_b32_e32 v58, v2
	v_mov_b32_e32 v59, v2
	v_mov_b32_e32 v60, v2
	v_mov_b32_e32 v61, v2
	v_mov_b32_e32 v62, v2
	v_mov_b32_e32 v63, v2
	v_mov_b32_e32 v64, v2
	v_mov_b32_e32 v65, v2
	v_mov_b32_e32 v66, v2
	v_mov_b32_e32 v67, v2
	v_mov_b32_e32 v68, v2
	v_mov_b32_e32 v69, v2
	v_mov_b32_e32 v70, v2
	v_mov_b32_e32 v71, v2
	v_mov_b32_e32 v72, v2
	v_mov_b32_e32 v73, v2
	v_mov_b32_e32 v82, v2
	v_mov_b32_e32 v83, v2
	v_mov_b32_e32 v84, v2
	v_mov_b32_e32 v85, v2
	v_mov_b32_e32 v86, v2
	v_mov_b32_e32 v87, v2
	v_mov_b32_e32 v88, v2
	v_mov_b32_e32 v89, v2
	v_mov_b32_e32 v98, v2
	v_mov_b32_e32 v99, v2
	v_mov_b32_e32 v100, v2
	v_mov_b32_e32 v101, v2
	v_mov_b32_e32 v102, v2
	v_mov_b32_e32 v103, v2
	v_mov_b32_e32 v104, v2
	v_mov_b32_e32 v105, v2
	v_mov_b32_e32 v114, v2
	v_mov_b32_e32 v115, v2
	v_mov_b32_e32 v116, v2
	v_mov_b32_e32 v117, v2
	v_mov_b32_e32 v118, v2
	v_mov_b32_e32 v119, v2
	v_mov_b32_e32 v120, v2
	v_mov_b32_e32 v121, v2
	v_mov_b32_e32 v74, v2
	v_mov_b32_e32 v75, v2
	v_mov_b32_e32 v76, v2
	v_mov_b32_e32 v77, v2
	v_mov_b32_e32 v78, v2
	v_mov_b32_e32 v79, v2
	v_mov_b32_e32 v80, v2
	v_mov_b32_e32 v81, v2
	v_mov_b32_e32 v90, v2
	v_mov_b32_e32 v91, v2
	v_mov_b32_e32 v92, v2
	v_mov_b32_e32 v93, v2
	v_mov_b32_e32 v94, v2
	v_mov_b32_e32 v95, v2
	v_mov_b32_e32 v96, v2
	v_mov_b32_e32 v97, v2
	v_mov_b32_e32 v106, v2
	v_mov_b32_e32 v107, v2
	v_mov_b32_e32 v108, v2
	v_mov_b32_e32 v109, v2
	v_mov_b32_e32 v110, v2
	v_mov_b32_e32 v111, v2
	v_mov_b32_e32 v112, v2
	v_mov_b32_e32 v113, v2
	v_mov_b32_e32 v122, v2
	v_mov_b32_e32 v123, v2
	v_mov_b32_e32 v124, v2
	v_mov_b32_e32 v125, v2
	v_mov_b32_e32 v126, v2
	v_mov_b32_e32 v127, v2
	v_mov_b32_e32 v128, v2
	v_mov_b32_e32 v129, v2
	s_cmp_lg_u32 s98, 0
	s_cbranch_scc1 .Lrwp6_first
.LBB0_780:
	ds_read_b128 v[156:159], v152
	ds_read_b128 v[160:163], v152 offset:1024
	ds_read_b128 v[164:167], v152 offset:2048
	ds_read_b128 v[168:171], v152 offset:3072
	ds_read_b128 v[172:175], v153
	ds_read_b128 v[176:179], v153 offset:1024
	ds_read_b128 v[180:183], v153 offset:2048
	ds_read_b128 v[184:187], v153 offset:3072
	s_add_u32 s6, s48, 0xfffc0080
	s_addc_u32 s7, s49, -1
	s_cmp_eq_u32 s82, 12
	s_cselect_b32 s53, s43, s7
	s_cselect_b32 s52, s78, s6
	s_cselect_b32 s51, s39, s81
	s_cselect_b32 s50, s79, s80
	v_lshl_add_u64 v[148:149], s[48:49], 0, v[140:141]
	s_add_i32 m0, s54, 0xc000
	ds_read_b128 v[188:191], v154
	ds_read_b128 v[192:195], v154 offset:1024
	ds_read_b128 v[196:199], v154 offset:2048
	ds_read_b128 v[200:203], v154 offset:3072
	ds_read_b128 v[204:207], v154 offset:4096
	ds_read_b128 v[208:211], v154 offset:5120
	ds_read_b128 v[212:215], v154 offset:6144
	ds_read_b128 v[216:219], v154 offset:7168
	global_load_lds_dwordx4 v[148:149], off
	v_lshl_add_u64 v[148:149], s[48:49], 0, v[142:143]
	s_add_i32 m0, s54, 0xe000
	s_nop 0
	global_load_lds_dwordx4 v[148:149], off
	s_waitcnt vmcnt(8)
	s_waitcnt lgkmcnt(0)
	s_barrier
	s_setprio 1
	s_waitcnt lgkmcnt(0)
	v_mfma_f32_16x16x32_bf16 v[126:129], v[156:159], v[188:191], v[126:129]
	v_mfma_f32_16x16x32_bf16 v[122:125], v[164:167], v[188:191], v[122:125]
	v_mfma_f32_16x16x32_bf16 v[110:113], v[156:159], v[196:199], v[110:113]
	v_mfma_f32_16x16x32_bf16 v[106:109], v[164:167], v[196:199], v[106:109]
	v_mfma_f32_16x16x32_bf16 v[94:97], v[156:159], v[204:207], v[94:97]
	v_mfma_f32_16x16x32_bf16 v[90:93], v[164:167], v[204:207], v[90:93]
	v_mfma_f32_16x16x32_bf16 v[78:81], v[156:159], v[212:215], v[78:81]
	v_mfma_f32_16x16x32_bf16 v[74:77], v[164:167], v[212:215], v[74:77]
	v_mfma_f32_16x16x32_bf16 v[126:129], v[160:163], v[192:195], v[126:129]
	v_mfma_f32_16x16x32_bf16 v[122:125], v[168:171], v[192:195], v[122:125]
	v_mfma_f32_16x16x32_bf16 v[110:113], v[160:163], v[200:203], v[110:113]
	v_mfma_f32_16x16x32_bf16 v[106:109], v[168:171], v[200:203], v[106:109]
	v_mfma_f32_16x16x32_bf16 v[94:97], v[160:163], v[208:211], v[94:97]
	v_mfma_f32_16x16x32_bf16 v[90:93], v[168:171], v[208:211], v[90:93]
	v_mfma_f32_16x16x32_bf16 v[78:81], v[160:163], v[216:219], v[78:81]
	v_mfma_f32_16x16x32_bf16 v[74:77], v[168:171], v[216:219], v[74:77]
	s_setprio 0
	s_setprio 1
	v_mfma_f32_16x16x32_bf16 v[118:121], v[172:175], v[188:191], v[118:121]
	v_mfma_f32_16x16x32_bf16 v[114:117], v[180:183], v[188:191], v[114:117]
	v_mfma_f32_16x16x32_bf16 v[102:105], v[172:175], v[196:199], v[102:105]
	v_mfma_f32_16x16x32_bf16 v[98:101], v[180:183], v[196:199], v[98:101]
	v_mfma_f32_16x16x32_bf16 v[86:89], v[172:175], v[204:207], v[86:89]
	v_mfma_f32_16x16x32_bf16 v[82:85], v[180:183], v[204:207], v[82:85]
	v_mfma_f32_16x16x32_bf16 v[70:73], v[172:175], v[212:215], v[70:73]
	v_mfma_f32_16x16x32_bf16 v[66:69], v[180:183], v[212:215], v[66:69]
	v_mfma_f32_16x16x32_bf16 v[118:121], v[176:179], v[192:195], v[118:121]
	v_mfma_f32_16x16x32_bf16 v[114:117], v[184:187], v[192:195], v[114:117]
	v_mfma_f32_16x16x32_bf16 v[102:105], v[176:179], v[200:203], v[102:105]
	v_mfma_f32_16x16x32_bf16 v[98:101], v[184:187], v[200:203], v[98:101]
	v_mfma_f32_16x16x32_bf16 v[86:89], v[176:179], v[208:211], v[86:89]
	v_mfma_f32_16x16x32_bf16 v[82:85], v[184:187], v[208:211], v[82:85]
	v_mfma_f32_16x16x32_bf16 v[70:73], v[176:179], v[216:219], v[70:73]
	v_mfma_f32_16x16x32_bf16 v[66:69], v[184:187], v[216:219], v[66:69]
	s_setprio 0
	s_barrier
	s_add_i32 s6, s63, s31
	v_lshl_add_u64 v[148:149], s[50:51], 0, v[132:133]
	s_mov_b32 m0, s6
	ds_read_b128 v[188:191], v154 offset:16384
	ds_read_b128 v[192:195], v154 offset:17408
	ds_read_b128 v[196:199], v154 offset:18432
	ds_read_b128 v[200:203], v154 offset:19456
	ds_read_b128 v[204:207], v154 offset:20480
	ds_read_b128 v[208:211], v154 offset:21504
	ds_read_b128 v[212:215], v154 offset:22528
	ds_read_b128 v[216:219], v154 offset:23552
	global_load_lds_dwordx4 v[148:149], off
	s_add_i32 m0, s6, 0x2000
	s_add_u32 s6, s50, 0x40000
	v_lshl_add_u64 v[220:221], s[50:51], 0, v[136:137]
	s_addc_u32 s7, s51, 0
	s_add_i32 s83, s64, s31
	global_load_lds_dwordx4 v[220:221], off
	v_lshl_add_u64 v[222:223], s[6:7], 0, v[132:133]
	s_mov_b32 m0, s83
	v_lshl_add_u64 v[224:225], s[52:53], 0, v[134:135]
	global_load_lds_dwordx4 v[222:223], off
	v_lshl_add_u64 v[222:223], s[6:7], 0, v[136:137]
	s_add_i32 m0, s83, 0x2000
	s_nop 0
	global_load_lds_dwordx4 v[222:223], off
	v_lshl_add_u64 v[222:223], s[52:53], 0, v[130:131]
	s_mov_b32 m0, s54
	s_nop 0
	global_load_lds_dwordx4 v[222:223], off
	s_mov_b32 m0, s55
	s_nop 0
	global_load_lds_dwordx4 v[224:225], off
	s_waitcnt vmcnt(8)
	s_waitcnt lgkmcnt(0)
	s_barrier
	s_setprio 1
	s_waitcnt lgkmcnt(0)
	v_mfma_f32_16x16x32_bf16 v[62:65], v[156:159], v[188:191], v[62:65]
	v_mfma_f32_16x16x32_bf16 v[58:61], v[164:167], v[188:191], v[58:61]
	v_mfma_f32_16x16x32_bf16 v[46:49], v[156:159], v[196:199], v[46:49]
	v_mfma_f32_16x16x32_bf16 v[42:45], v[164:167], v[196:199], v[42:45]
	v_mfma_f32_16x16x32_bf16 v[30:33], v[156:159], v[204:207], v[30:33]
	v_mfma_f32_16x16x32_bf16 v[26:29], v[164:167], v[204:207], v[26:29]
	v_mfma_f32_16x16x32_bf16 v[14:17], v[156:159], v[212:215], v[14:17]
	v_mfma_f32_16x16x32_bf16 v[10:13], v[164:167], v[212:215], v[10:13]
	v_mfma_f32_16x16x32_bf16 v[62:65], v[160:163], v[192:195], v[62:65]
	v_mfma_f32_16x16x32_bf16 v[58:61], v[168:171], v[192:195], v[58:61]
	v_mfma_f32_16x16x32_bf16 v[46:49], v[160:163], v[200:203], v[46:49]
	v_mfma_f32_16x16x32_bf16 v[42:45], v[168:171], v[200:203], v[42:45]
	v_mfma_f32_16x16x32_bf16 v[30:33], v[160:163], v[208:211], v[30:33]
	v_mfma_f32_16x16x32_bf16 v[26:29], v[168:171], v[208:211], v[26:29]
	v_mfma_f32_16x16x32_bf16 v[14:17], v[160:163], v[216:219], v[14:17]
	v_mfma_f32_16x16x32_bf16 v[10:13], v[168:171], v[216:219], v[10:13]
	s_setprio 0
	s_setprio 1
	v_mfma_f32_16x16x32_bf16 v[54:57], v[172:175], v[188:191], v[54:57]
	v_mfma_f32_16x16x32_bf16 v[50:53], v[180:183], v[188:191], v[50:53]
	v_mfma_f32_16x16x32_bf16 v[38:41], v[172:175], v[196:199], v[38:41]
	v_mfma_f32_16x16x32_bf16 v[34:37], v[180:183], v[196:199], v[34:37]
	v_mfma_f32_16x16x32_bf16 v[22:25], v[172:175], v[204:207], v[22:25]
	v_mfma_f32_16x16x32_bf16 v[18:21], v[180:183], v[204:207], v[18:21]
	v_mfma_f32_16x16x32_bf16 v[6:9], v[172:175], v[212:215], v[6:9]
	v_mfma_f32_16x16x32_bf16 v[2:5], v[180:183], v[212:215], v[2:5]
	v_mfma_f32_16x16x32_bf16 v[54:57], v[176:179], v[192:195], v[54:57]
	v_mfma_f32_16x16x32_bf16 v[50:53], v[184:187], v[192:195], v[50:53]
	v_mfma_f32_16x16x32_bf16 v[38:41], v[176:179], v[200:203], v[38:41]
	v_mfma_f32_16x16x32_bf16 v[34:37], v[184:187], v[200:203], v[34:37]
	v_mfma_f32_16x16x32_bf16 v[22:25], v[176:179], v[208:211], v[22:25]
	v_mfma_f32_16x16x32_bf16 v[18:21], v[184:187], v[208:211], v[18:21]
	v_mfma_f32_16x16x32_bf16 v[6:9], v[176:179], v[216:219], v[6:9]
	v_mfma_f32_16x16x32_bf16 v[2:5], v[184:187], v[216:219], v[2:5]
	s_setprio 0
	s_barrier
	s_add_i32 s83, 0, 0x18000
	v_add_u32_e32 v138, s83, v151
	s_add_i32 s84, 0, 0x1c000
	ds_read_b128 v[156:159], v138
	ds_read_b128 v[160:163], v138 offset:1024
	ds_read_b128 v[164:167], v138 offset:2048
	ds_read_b128 v[168:171], v138 offset:3072
	v_add_u32_e32 v138, s84, v151
	ds_read_b128 v[172:175], v138
	ds_read_b128 v[176:179], v138 offset:1024
	ds_read_b128 v[180:183], v138 offset:2048
	ds_read_b128 v[184:187], v138 offset:3072
	s_add_u32 s6, s52, 0x40000
	s_addc_u32 s7, s53, 0
	s_mov_b32 m0, s56
	v_lshl_add_u64 v[226:227], s[6:7], 0, v[130:131]
	ds_read_b128 v[188:191], v154 offset:32768
	ds_read_b128 v[192:195], v154 offset:33792
	ds_read_b128 v[196:199], v154 offset:34816
	ds_read_b128 v[200:203], v154 offset:35840
	ds_read_b128 v[204:207], v154 offset:36864
	ds_read_b128 v[208:211], v154 offset:37888
	ds_read_b128 v[212:215], v154 offset:38912
	ds_read_b128 v[216:219], v154 offset:39936
	global_load_lds_dwordx4 v[226:227], off
	v_lshl_add_u64 v[226:227], s[6:7], 0, v[134:135]
	s_mov_b32 m0, s57
	s_nop 0
	global_load_lds_dwordx4 v[226:227], off
	s_waitcnt vmcnt(8)
	s_waitcnt lgkmcnt(0)
	s_barrier
	s_setprio 1
	s_waitcnt lgkmcnt(0)
	v_mfma_f32_16x16x32_bf16 v[126:129], v[156:159], v[188:191], v[126:129]
	v_mfma_f32_16x16x32_bf16 v[122:125], v[164:167], v[188:191], v[122:125]
	v_mfma_f32_16x16x32_bf16 v[110:113], v[156:159], v[196:199], v[110:113]
	v_mfma_f32_16x16x32_bf16 v[106:109], v[164:167], v[196:199], v[106:109]
	v_mfma_f32_16x16x32_bf16 v[94:97], v[156:159], v[204:207], v[94:97]
	v_mfma_f32_16x16x32_bf16 v[90:93], v[164:167], v[204:207], v[90:93]
	v_mfma_f32_16x16x32_bf16 v[78:81], v[156:159], v[212:215], v[78:81]
	v_mfma_f32_16x16x32_bf16 v[74:77], v[164:167], v[212:215], v[74:77]
	v_mfma_f32_16x16x32_bf16 v[126:129], v[160:163], v[192:195], v[126:129]
	v_mfma_f32_16x16x32_bf16 v[122:125], v[168:171], v[192:195], v[122:125]
	v_mfma_f32_16x16x32_bf16 v[110:113], v[160:163], v[200:203], v[110:113]
	v_mfma_f32_16x16x32_bf16 v[106:109], v[168:171], v[200:203], v[106:109]
	v_mfma_f32_16x16x32_bf16 v[94:97], v[160:163], v[208:211], v[94:97]
	v_mfma_f32_16x16x32_bf16 v[90:93], v[168:171], v[208:211], v[90:93]
	v_mfma_f32_16x16x32_bf16 v[78:81], v[160:163], v[216:219], v[78:81]
	v_mfma_f32_16x16x32_bf16 v[74:77], v[168:171], v[216:219], v[74:77]
	s_setprio 0
	s_setprio 1
	v_mfma_f32_16x16x32_bf16 v[118:121], v[172:175], v[188:191], v[118:121]
	v_mfma_f32_16x16x32_bf16 v[114:117], v[180:183], v[188:191], v[114:117]
	v_mfma_f32_16x16x32_bf16 v[102:105], v[172:175], v[196:199], v[102:105]
	v_mfma_f32_16x16x32_bf16 v[98:101], v[180:183], v[196:199], v[98:101]
	v_mfma_f32_16x16x32_bf16 v[86:89], v[172:175], v[204:207], v[86:89]
	v_mfma_f32_16x16x32_bf16 v[82:85], v[180:183], v[204:207], v[82:85]
	v_mfma_f32_16x16x32_bf16 v[70:73], v[172:175], v[212:215], v[70:73]
	v_mfma_f32_16x16x32_bf16 v[66:69], v[180:183], v[212:215], v[66:69]
	v_mfma_f32_16x16x32_bf16 v[118:121], v[176:179], v[192:195], v[118:121]
	v_mfma_f32_16x16x32_bf16 v[114:117], v[184:187], v[192:195], v[114:117]
	v_mfma_f32_16x16x32_bf16 v[102:105], v[176:179], v[200:203], v[102:105]
	v_mfma_f32_16x16x32_bf16 v[98:101], v[184:187], v[200:203], v[98:101]
	v_mfma_f32_16x16x32_bf16 v[86:89], v[176:179], v[208:211], v[86:89]
	v_mfma_f32_16x16x32_bf16 v[82:85], v[184:187], v[208:211], v[82:85]
	v_mfma_f32_16x16x32_bf16 v[70:73], v[176:179], v[216:219], v[70:73]
	v_mfma_f32_16x16x32_bf16 v[66:69], v[184:187], v[216:219], v[66:69]
	s_setprio 0
	s_barrier
	s_add_i32 s6, s83, s31
	v_lshl_add_u64 v[148:149], v[148:149], 0, s[16:17]
	s_mov_b32 m0, s6
	ds_read_b128 v[188:191], v154 offset:49152
	ds_read_b128 v[192:195], v154 offset:50176
	ds_read_b128 v[196:199], v154 offset:51200
	ds_read_b128 v[200:203], v154 offset:52224
	ds_read_b128 v[204:207], v154 offset:53248
	ds_read_b128 v[208:211], v154 offset:54272
	ds_read_b128 v[212:215], v154 offset:55296
	ds_read_b128 v[216:219], v154 offset:56320
	global_load_lds_dwordx4 v[148:149], off
	s_add_i32 m0, s6, 0x2000
	s_add_u32 s6, s50, 0x40080
	v_lshl_add_u64 v[148:149], v[220:221], 0, s[16:17]
	s_addc_u32 s7, s51, 0
	s_add_i32 s50, s84, s31
	global_load_lds_dwordx4 v[148:149], off
	v_lshl_add_u64 v[148:149], s[6:7], 0, v[132:133]
	s_mov_b32 m0, s50
	s_nop 0
	global_load_lds_dwordx4 v[148:149], off
	v_lshl_add_u64 v[148:149], s[6:7], 0, v[136:137]
	s_add_i32 m0, s50, 0x2000
	s_nop 0
	global_load_lds_dwordx4 v[148:149], off
	v_lshl_add_u64 v[148:149], v[222:223], 0, s[16:17]
	s_mov_b32 m0, s60
	s_nop 0
	global_load_lds_dwordx4 v[148:149], off
	v_lshl_add_u64 v[148:149], v[224:225], 0, s[16:17]
	s_mov_b32 m0, s61
	s_nop 0
	global_load_lds_dwordx4 v[148:149], off
	s_waitcnt vmcnt(8)
	s_waitcnt lgkmcnt(0)
	s_barrier
	s_setprio 1
	s_waitcnt lgkmcnt(0)
	v_mfma_f32_16x16x32_bf16 v[62:65], v[156:159], v[188:191], v[62:65]
	v_mfma_f32_16x16x32_bf16 v[58:61], v[164:167], v[188:191], v[58:61]
	v_mfma_f32_16x16x32_bf16 v[46:49], v[156:159], v[196:199], v[46:49]
	v_mfma_f32_16x16x32_bf16 v[42:45], v[164:167], v[196:199], v[42:45]
	v_mfma_f32_16x16x32_bf16 v[30:33], v[156:159], v[204:207], v[30:33]
	v_mfma_f32_16x16x32_bf16 v[26:29], v[164:167], v[204:207], v[26:29]
	v_mfma_f32_16x16x32_bf16 v[14:17], v[156:159], v[212:215], v[14:17]
	v_mfma_f32_16x16x32_bf16 v[10:13], v[164:167], v[212:215], v[10:13]
	v_mfma_f32_16x16x32_bf16 v[62:65], v[160:163], v[192:195], v[62:65]
	v_mfma_f32_16x16x32_bf16 v[58:61], v[168:171], v[192:195], v[58:61]
	v_mfma_f32_16x16x32_bf16 v[46:49], v[160:163], v[200:203], v[46:49]
	v_mfma_f32_16x16x32_bf16 v[42:45], v[168:171], v[200:203], v[42:45]
	v_mfma_f32_16x16x32_bf16 v[30:33], v[160:163], v[208:211], v[30:33]
	v_mfma_f32_16x16x32_bf16 v[26:29], v[168:171], v[208:211], v[26:29]
	v_mfma_f32_16x16x32_bf16 v[14:17], v[160:163], v[216:219], v[14:17]
	v_mfma_f32_16x16x32_bf16 v[10:13], v[168:171], v[216:219], v[10:13]
	s_setprio 0
	s_setprio 1
	v_mfma_f32_16x16x32_bf16 v[54:57], v[172:175], v[188:191], v[54:57]
	v_mfma_f32_16x16x32_bf16 v[50:53], v[180:183], v[188:191], v[50:53]
	v_mfma_f32_16x16x32_bf16 v[38:41], v[172:175], v[196:199], v[38:41]
	v_mfma_f32_16x16x32_bf16 v[34:37], v[180:183], v[196:199], v[34:37]
	v_mfma_f32_16x16x32_bf16 v[22:25], v[172:175], v[204:207], v[22:25]
	v_mfma_f32_16x16x32_bf16 v[18:21], v[180:183], v[204:207], v[18:21]
	v_mfma_f32_16x16x32_bf16 v[6:9], v[172:175], v[212:215], v[6:9]
	v_mfma_f32_16x16x32_bf16 v[2:5], v[180:183], v[212:215], v[2:5]
	v_mfma_f32_16x16x32_bf16 v[54:57], v[176:179], v[192:195], v[54:57]
	v_mfma_f32_16x16x32_bf16 v[50:53], v[184:187], v[192:195], v[50:53]
	v_mfma_f32_16x16x32_bf16 v[38:41], v[176:179], v[200:203], v[38:41]
	v_mfma_f32_16x16x32_bf16 v[34:37], v[184:187], v[200:203], v[34:37]
	v_mfma_f32_16x16x32_bf16 v[22:25], v[176:179], v[208:211], v[22:25]
	v_mfma_f32_16x16x32_bf16 v[18:21], v[184:187], v[208:211], v[18:21]
	v_mfma_f32_16x16x32_bf16 v[6:9], v[176:179], v[216:219], v[6:9]
	v_mfma_f32_16x16x32_bf16 v[2:5], v[184:187], v[216:219], v[2:5]
	s_setprio 0
	s_barrier
	s_add_i32 s82, s82, 2
	s_add_u32 s48, s48, 0x100
	s_addc_u32 s49, s49, 0
	s_add_u32 s80, s80, 0x100
	s_addc_u32 s81, s81, 0
	s_cmp_gt_u32 s82, 13
	s_cbranch_scc0 .LBB0_780
.Lrwp6_exit:
	s_and_b64 vcc, exec, s[36:37]
	s_cbranch_vccz .LBB0_783
	s_barrier

.Lrwp6_first:
	ds_read_b128 v[156:159], v152
	ds_read_b128 v[160:163], v152 offset:1024
	ds_read_b128 v[164:167], v152 offset:2048
	ds_read_b128 v[168:171], v152 offset:3072
	ds_read_b128 v[172:175], v153
	ds_read_b128 v[176:179], v153 offset:1024
	ds_read_b128 v[180:183], v153 offset:2048
	ds_read_b128 v[184:187], v153 offset:3072
	s_add_u32 s6, s48, 0xfffc0080
	s_addc_u32 s7, s49, -1
	s_cmp_eq_u32 s82, 12
	s_cselect_b32 s53, s43, s7
	s_cselect_b32 s52, s78, s6
	s_cselect_b32 s51, s39, s81
	s_cselect_b32 s50, s79, s80
	v_lshl_add_u64 v[148:149], s[48:49], 0, v[140:141]
	s_add_i32 m0, s54, 0xc000
	ds_read_b128 v[188:191], v154
	ds_read_b128 v[192:195], v154 offset:1024
	ds_read_b128 v[196:199], v154 offset:2048
	ds_read_b128 v[200:203], v154 offset:3072
	ds_read_b128 v[204:207], v154 offset:4096
	ds_read_b128 v[208:211], v154 offset:5120
	ds_read_b128 v[212:215], v154 offset:6144
	ds_read_b128 v[216:219], v154 offset:7168
	global_load_lds_dwordx4 v[148:149], off
	v_lshl_add_u64 v[148:149], s[48:49], 0, v[142:143]
	s_add_i32 m0, s54, 0xe000
	s_nop 0
	global_load_lds_dwordx4 v[148:149], off
	s_cmp_eq_u32 s98, 1
	s_cbranch_scc1 .Lrwp6_a16
	s_waitcnt vmcnt(8)
	s_branch .Lrwp6_adone

.Lrwp6_adone:
	s_waitcnt lgkmcnt(0)
	s_barrier
	s_setprio 1
	s_waitcnt lgkmcnt(0)
	v_mfma_f32_16x16x32_bf16 v[126:129], v[156:159], v[188:191], v[126:129]
	v_mfma_f32_16x16x32_bf16 v[122:125], v[164:167], v[188:191], v[122:125]
	v_mfma_f32_16x16x32_bf16 v[110:113], v[156:159], v[196:199], v[110:113]
	v_mfma_f32_16x16x32_bf16 v[106:109], v[164:167], v[196:199], v[106:109]
	v_mfma_f32_16x16x32_bf16 v[94:97], v[156:159], v[204:207], v[94:97]
	v_mfma_f32_16x16x32_bf16 v[90:93], v[164:167], v[204:207], v[90:93]
	v_mfma_f32_16x16x32_bf16 v[78:81], v[156:159], v[212:215], v[78:81]
	v_mfma_f32_16x16x32_bf16 v[74:77], v[164:167], v[212:215], v[74:77]
	v_mfma_f32_16x16x32_bf16 v[126:129], v[160:163], v[192:195], v[126:129]
	v_mfma_f32_16x16x32_bf16 v[122:125], v[168:171], v[192:195], v[122:125]
	v_mfma_f32_16x16x32_bf16 v[110:113], v[160:163], v[200:203], v[110:113]
	v_mfma_f32_16x16x32_bf16 v[106:109], v[168:171], v[200:203], v[106:109]
	v_mfma_f32_16x16x32_bf16 v[94:97], v[160:163], v[208:211], v[94:97]
	v_mfma_f32_16x16x32_bf16 v[90:93], v[168:171], v[208:211], v[90:93]
	v_mfma_f32_16x16x32_bf16 v[78:81], v[160:163], v[216:219], v[78:81]
	v_mfma_f32_16x16x32_bf16 v[74:77], v[168:171], v[216:219], v[74:77]
	s_setprio 0
	s_setprio 1
	v_mfma_f32_16x16x32_bf16 v[118:121], v[172:175], v[188:191], v[118:121]
	v_mfma_f32_16x16x32_bf16 v[114:117], v[180:183], v[188:191], v[114:117]
	v_mfma_f32_16x16x32_bf16 v[102:105], v[172:175], v[196:199], v[102:105]
	v_mfma_f32_16x16x32_bf16 v[98:101], v[180:183], v[196:199], v[98:101]
	v_mfma_f32_16x16x32_bf16 v[86:89], v[172:175], v[204:207], v[86:89]
	v_mfma_f32_16x16x32_bf16 v[82:85], v[180:183], v[204:207], v[82:85]
	v_mfma_f32_16x16x32_bf16 v[70:73], v[172:175], v[212:215], v[70:73]
	v_mfma_f32_16x16x32_bf16 v[66:69], v[180:183], v[212:215], v[66:69]
	v_mfma_f32_16x16x32_bf16 v[118:121], v[176:179], v[192:195], v[118:121]
	v_mfma_f32_16x16x32_bf16 v[114:117], v[184:187], v[192:195], v[114:117]
	v_mfma_f32_16x16x32_bf16 v[102:105], v[176:179], v[200:203], v[102:105]
	v_mfma_f32_16x16x32_bf16 v[98:101], v[184:187], v[200:203], v[98:101]
	v_mfma_f32_16x16x32_bf16 v[86:89], v[176:179], v[208:211], v[86:89]
	v_mfma_f32_16x16x32_bf16 v[82:85], v[184:187], v[208:211], v[82:85]
	v_mfma_f32_16x16x32_bf16 v[70:73], v[176:179], v[216:219], v[70:73]
	v_mfma_f32_16x16x32_bf16 v[66:69], v[184:187], v[216:219], v[66:69]
	s_setprio 0
	s_barrier
	s_add_i32 s6, s63, s31
	v_lshl_add_u64 v[148:149], s[50:51], 0, v[132:133]
	s_mov_b32 m0, s6
	ds_read_b128 v[188:191], v154 offset:16384
	ds_read_b128 v[192:195], v154 offset:17408
	ds_read_b128 v[196:199], v154 offset:18432
	ds_read_b128 v[200:203], v154 offset:19456
	ds_read_b128 v[204:207], v154 offset:20480
	ds_read_b128 v[208:211], v154 offset:21504
	ds_read_b128 v[212:215], v154 offset:22528
	ds_read_b128 v[216:219], v154 offset:23552
	global_load_lds_dwordx4 v[148:149], off
	s_add_i32 m0, s6, 0x2000
	s_add_u32 s6, s50, 0x40000
	v_lshl_add_u64 v[220:221], s[50:51], 0, v[136:137]
	s_addc_u32 s7, s51, 0
	s_add_i32 s83, s64, s31
	global_load_lds_dwordx4 v[220:221], off
	v_lshl_add_u64 v[222:223], s[6:7], 0, v[132:133]
	s_mov_b32 m0, s83
	v_lshl_add_u64 v[224:225], s[52:53], 0, v[134:135]
	global_load_lds_dwordx4 v[222:223], off
	v_lshl_add_u64 v[222:223], s[6:7], 0, v[136:137]
	s_add_i32 m0, s83, 0x2000
	s_nop 0
	global_load_lds_dwordx4 v[222:223], off
	v_lshl_add_u64 v[222:223], s[52:53], 0, v[130:131]
	s_mov_b32 m0, s54
	s_nop 0
	global_load_lds_dwordx4 v[222:223], off
	s_mov_b32 m0, s55
	s_nop 0
	global_load_lds_dwordx4 v[224:225], off
	s_cmp_eq_u32 s98, 1
	s_cbranch_scc1 .Lrwp6_b16
	s_waitcnt vmcnt(8)
	s_branch .Lrwp6_bdone

.Lrwp6_bdone:
	s_mov_b32 s98, 0
	s_waitcnt lgkmcnt(0)
	s_barrier
	s_setprio 1
	s_waitcnt lgkmcnt(0)
	v_mfma_f32_16x16x32_bf16 v[62:65], v[156:159], v[188:191], v[62:65]
	v_mfma_f32_16x16x32_bf16 v[58:61], v[164:167], v[188:191], v[58:61]
	v_mfma_f32_16x16x32_bf16 v[46:49], v[156:159], v[196:199], v[46:49]
	v_mfma_f32_16x16x32_bf16 v[42:45], v[164:167], v[196:199], v[42:45]
	v_mfma_f32_16x16x32_bf16 v[30:33], v[156:159], v[204:207], v[30:33]
	v_mfma_f32_16x16x32_bf16 v[26:29], v[164:167], v[204:207], v[26:29]
	v_mfma_f32_16x16x32_bf16 v[14:17], v[156:159], v[212:215], v[14:17]
	v_mfma_f32_16x16x32_bf16 v[10:13], v[164:167], v[212:215], v[10:13]
	v_mfma_f32_16x16x32_bf16 v[62:65], v[160:163], v[192:195], v[62:65]
	v_mfma_f32_16x16x32_bf16 v[58:61], v[168:171], v[192:195], v[58:61]
	v_mfma_f32_16x16x32_bf16 v[46:49], v[160:163], v[200:203], v[46:49]
	v_mfma_f32_16x16x32_bf16 v[42:45], v[168:171], v[200:203], v[42:45]
	v_mfma_f32_16x16x32_bf16 v[30:33], v[160:163], v[208:211], v[30:33]
	v_mfma_f32_16x16x32_bf16 v[26:29], v[168:171], v[208:211], v[26:29]
	v_mfma_f32_16x16x32_bf16 v[14:17], v[160:163], v[216:219], v[14:17]
	v_mfma_f32_16x16x32_bf16 v[10:13], v[168:171], v[216:219], v[10:13]
	s_setprio 0
	s_setprio 1
	v_mfma_f32_16x16x32_bf16 v[54:57], v[172:175], v[188:191], v[54:57]
	v_mfma_f32_16x16x32_bf16 v[50:53], v[180:183], v[188:191], v[50:53]
	v_mfma_f32_16x16x32_bf16 v[38:41], v[172:175], v[196:199], v[38:41]
	v_mfma_f32_16x16x32_bf16 v[34:37], v[180:183], v[196:199], v[34:37]
	v_mfma_f32_16x16x32_bf16 v[22:25], v[172:175], v[204:207], v[22:25]
	v_mfma_f32_16x16x32_bf16 v[18:21], v[180:183], v[204:207], v[18:21]
	v_mfma_f32_16x16x32_bf16 v[6:9], v[172:175], v[212:215], v[6:9]
	v_mfma_f32_16x16x32_bf16 v[2:5], v[180:183], v[212:215], v[2:5]
	v_mfma_f32_16x16x32_bf16 v[54:57], v[176:179], v[192:195], v[54:57]
	v_mfma_f32_16x16x32_bf16 v[50:53], v[184:187], v[192:195], v[50:53]
	v_mfma_f32_16x16x32_bf16 v[38:41], v[176:179], v[200:203], v[38:41]
	v_mfma_f32_16x16x32_bf16 v[34:37], v[184:187], v[200:203], v[34:37]
	v_mfma_f32_16x16x32_bf16 v[22:25], v[176:179], v[208:211], v[22:25]
	v_mfma_f32_16x16x32_bf16 v[18:21], v[184:187], v[208:211], v[18:21]
	v_mfma_f32_16x16x32_bf16 v[6:9], v[176:179], v[216:219], v[6:9]
	v_mfma_f32_16x16x32_bf16 v[2:5], v[184:187], v[216:219], v[2:5]
	s_setprio 0
	s_barrier
	s_add_i32 s83, 0, 0x18000
	v_add_u32_e32 v138, s83, v151
	s_add_i32 s84, 0, 0x1c000
	ds_read_b128 v[156:159], v138
	ds_read_b128 v[160:163], v138 offset:1024
	ds_read_b128 v[164:167], v138 offset:2048
	ds_read_b128 v[168:171], v138 offset:3072
	v_add_u32_e32 v138, s84, v151
	ds_read_b128 v[172:175], v138
	ds_read_b128 v[176:179], v138 offset:1024
	ds_read_b128 v[180:183], v138 offset:2048
	ds_read_b128 v[184:187], v138 offset:3072
	s_add_u32 s6, s52, 0x40000
	s_addc_u32 s7, s53, 0
	s_mov_b32 m0, s56
	v_lshl_add_u64 v[226:227], s[6:7], 0, v[130:131]
	ds_read_b128 v[188:191], v154 offset:32768
	ds_read_b128 v[192:195], v154 offset:33792
	ds_read_b128 v[196:199], v154 offset:34816
	ds_read_b128 v[200:203], v154 offset:35840
	ds_read_b128 v[204:207], v154 offset:36864
	ds_read_b128 v[208:211], v154 offset:37888
	ds_read_b128 v[212:215], v154 offset:38912
	ds_read_b128 v[216:219], v154 offset:39936
	global_load_lds_dwordx4 v[226:227], off
	v_lshl_add_u64 v[226:227], s[6:7], 0, v[134:135]
	s_mov_b32 m0, s57
	s_nop 0
	global_load_lds_dwordx4 v[226:227], off
	s_waitcnt vmcnt(8)
	s_waitcnt lgkmcnt(0)
	s_barrier
	s_setprio 1
	s_waitcnt lgkmcnt(0)
	v_mfma_f32_16x16x32_bf16 v[126:129], v[156:159], v[188:191], v[126:129]
	v_mfma_f32_16x16x32_bf16 v[122:125], v[164:167], v[188:191], v[122:125]
	v_mfma_f32_16x16x32_bf16 v[110:113], v[156:159], v[196:199], v[110:113]
	v_mfma_f32_16x16x32_bf16 v[106:109], v[164:167], v[196:199], v[106:109]
	v_mfma_f32_16x16x32_bf16 v[94:97], v[156:159], v[204:207], v[94:97]
	v_mfma_f32_16x16x32_bf16 v[90:93], v[164:167], v[204:207], v[90:93]
	v_mfma_f32_16x16x32_bf16 v[78:81], v[156:159], v[212:215], v[78:81]
	v_mfma_f32_16x16x32_bf16 v[74:77], v[164:167], v[212:215], v[74:77]
	v_mfma_f32_16x16x32_bf16 v[126:129], v[160:163], v[192:195], v[126:129]
	v_mfma_f32_16x16x32_bf16 v[122:125], v[168:171], v[192:195], v[122:125]
	v_mfma_f32_16x16x32_bf16 v[110:113], v[160:163], v[200:203], v[110:113]
	v_mfma_f32_16x16x32_bf16 v[106:109], v[168:171], v[200:203], v[106:109]
	v_mfma_f32_16x16x32_bf16 v[94:97], v[160:163], v[208:211], v[94:97]
	v_mfma_f32_16x16x32_bf16 v[90:93], v[168:171], v[208:211], v[90:93]
	v_mfma_f32_16x16x32_bf16 v[78:81], v[160:163], v[216:219], v[78:81]
	v_mfma_f32_16x16x32_bf16 v[74:77], v[168:171], v[216:219], v[74:77]
	s_setprio 0
	s_setprio 1
	v_mfma_f32_16x16x32_bf16 v[118:121], v[172:175], v[188:191], v[118:121]
	v_mfma_f32_16x16x32_bf16 v[114:117], v[180:183], v[188:191], v[114:117]
	v_mfma_f32_16x16x32_bf16 v[102:105], v[172:175], v[196:199], v[102:105]
	v_mfma_f32_16x16x32_bf16 v[98:101], v[180:183], v[196:199], v[98:101]
	v_mfma_f32_16x16x32_bf16 v[86:89], v[172:175], v[204:207], v[86:89]
	v_mfma_f32_16x16x32_bf16 v[82:85], v[180:183], v[204:207], v[82:85]
	v_mfma_f32_16x16x32_bf16 v[70:73], v[172:175], v[212:215], v[70:73]
	v_mfma_f32_16x16x32_bf16 v[66:69], v[180:183], v[212:215], v[66:69]
	v_mfma_f32_16x16x32_bf16 v[118:121], v[176:179], v[192:195], v[118:121]
	v_mfma_f32_16x16x32_bf16 v[114:117], v[184:187], v[192:195], v[114:117]
	v_mfma_f32_16x16x32_bf16 v[102:105], v[176:179], v[200:203], v[102:105]
	v_mfma_f32_16x16x32_bf16 v[98:101], v[184:187], v[200:203], v[98:101]
	v_mfma_f32_16x16x32_bf16 v[86:89], v[176:179], v[208:211], v[86:89]
	v_mfma_f32_16x16x32_bf16 v[82:85], v[184:187], v[208:211], v[82:85]
	v_mfma_f32_16x16x32_bf16 v[70:73], v[176:179], v[216:219], v[70:73]
	v_mfma_f32_16x16x32_bf16 v[66:69], v[184:187], v[216:219], v[66:69]
	s_setprio 0
	s_barrier
	s_add_i32 s6, s83, s31
	v_lshl_add_u64 v[148:149], v[148:149], 0, s[16:17]
	s_mov_b32 m0, s6
	ds_read_b128 v[188:191], v154 offset:49152
	ds_read_b128 v[192:195], v154 offset:50176
	ds_read_b128 v[196:199], v154 offset:51200
	ds_read_b128 v[200:203], v154 offset:52224
	ds_read_b128 v[204:207], v154 offset:53248
	ds_read_b128 v[208:211], v154 offset:54272
	ds_read_b128 v[212:215], v154 offset:55296
	ds_read_b128 v[216:219], v154 offset:56320
	global_load_lds_dwordx4 v[148:149], off
	s_add_i32 m0, s6, 0x2000
	s_add_u32 s6, s50, 0x40080
	v_lshl_add_u64 v[148:149], v[220:221], 0, s[16:17]
	s_addc_u32 s7, s51, 0
	s_add_i32 s50, s84, s31
	global_load_lds_dwordx4 v[148:149], off
	v_lshl_add_u64 v[148:149], s[6:7], 0, v[132:133]
	s_mov_b32 m0, s50
	s_nop 0
	global_load_lds_dwordx4 v[148:149], off
	v_lshl_add_u64 v[148:149], s[6:7], 0, v[136:137]
	s_add_i32 m0, s50, 0x2000
	s_nop 0
	global_load_lds_dwordx4 v[148:149], off
	v_lshl_add_u64 v[148:149], v[222:223], 0, s[16:17]
	s_mov_b32 m0, s60
	s_nop 0
	global_load_lds_dwordx4 v[148:149], off
	v_lshl_add_u64 v[148:149], v[224:225], 0, s[16:17]
	s_mov_b32 m0, s61
	s_nop 0
	global_load_lds_dwordx4 v[148:149], off
	s_waitcnt vmcnt(8)
	s_waitcnt lgkmcnt(0)
	s_barrier
	s_setprio 1
	s_waitcnt lgkmcnt(0)
	v_mfma_f32_16x16x32_bf16 v[62:65], v[156:159], v[188:191], v[62:65]
	v_mfma_f32_16x16x32_bf16 v[58:61], v[164:167], v[188:191], v[58:61]
	v_mfma_f32_16x16x32_bf16 v[46:49], v[156:159], v[196:199], v[46:49]
	v_mfma_f32_16x16x32_bf16 v[42:45], v[164:167], v[196:199], v[42:45]
	v_mfma_f32_16x16x32_bf16 v[30:33], v[156:159], v[204:207], v[30:33]
	v_mfma_f32_16x16x32_bf16 v[26:29], v[164:167], v[204:207], v[26:29]
	v_mfma_f32_16x16x32_bf16 v[14:17], v[156:159], v[212:215], v[14:17]
	v_mfma_f32_16x16x32_bf16 v[10:13], v[164:167], v[212:215], v[10:13]
	v_mfma_f32_16x16x32_bf16 v[62:65], v[160:163], v[192:195], v[62:65]
	v_mfma_f32_16x16x32_bf16 v[58:61], v[168:171], v[192:195], v[58:61]
	v_mfma_f32_16x16x32_bf16 v[46:49], v[160:163], v[200:203], v[46:49]
	v_mfma_f32_16x16x32_bf16 v[42:45], v[168:171], v[200:203], v[42:45]
	v_mfma_f32_16x16x32_bf16 v[30:33], v[160:163], v[208:211], v[30:33]
	v_mfma_f32_16x16x32_bf16 v[26:29], v[168:171], v[208:211], v[26:29]
	v_mfma_f32_16x16x32_bf16 v[14:17], v[160:163], v[216:219], v[14:17]
	v_mfma_f32_16x16x32_bf16 v[10:13], v[168:171], v[216:219], v[10:13]
	s_setprio 0
	s_setprio 1
	v_mfma_f32_16x16x32_bf16 v[54:57], v[172:175], v[188:191], v[54:57]
	v_mfma_f32_16x16x32_bf16 v[50:53], v[180:183], v[188:191], v[50:53]
	v_mfma_f32_16x16x32_bf16 v[38:41], v[172:175], v[196:199], v[38:41]
	v_mfma_f32_16x16x32_bf16 v[34:37], v[180:183], v[196:199], v[34:37]
	v_mfma_f32_16x16x32_bf16 v[22:25], v[172:175], v[204:207], v[22:25]
	v_mfma_f32_16x16x32_bf16 v[18:21], v[180:183], v[204:207], v[18:21]
	v_mfma_f32_16x16x32_bf16 v[6:9], v[172:175], v[212:215], v[6:9]
	v_mfma_f32_16x16x32_bf16 v[2:5], v[180:183], v[212:215], v[2:5]
	v_mfma_f32_16x16x32_bf16 v[54:57], v[176:179], v[192:195], v[54:57]
	v_mfma_f32_16x16x32_bf16 v[50:53], v[184:187], v[192:195], v[50:53]
	v_mfma_f32_16x16x32_bf16 v[38:41], v[176:179], v[200:203], v[38:41]
	v_mfma_f32_16x16x32_bf16 v[34:37], v[184:187], v[200:203], v[34:37]
	v_mfma_f32_16x16x32_bf16 v[22:25], v[176:179], v[208:211], v[22:25]
	v_mfma_f32_16x16x32_bf16 v[18:21], v[184:187], v[208:211], v[18:21]
	v_mfma_f32_16x16x32_bf16 v[6:9], v[176:179], v[216:219], v[6:9]
	v_mfma_f32_16x16x32_bf16 v[2:5], v[184:187], v[216:219], v[2:5]
	s_setprio 0
	s_barrier
	s_add_i32 s82, s82, 2
	s_add_u32 s48, s48, 0x100
	s_addc_u32 s49, s49, 0
	s_add_u32 s80, s80, 0x100
	s_addc_u32 s81, s81, 0
	s_cmp_gt_u32 s82, 13
	s_cbranch_scc0 .LBB0_780
	s_branch .Lrwp6_exit
